# hgrn_sample: next task state loads prefetched before the reduction, reduction LDS reads batched
# speedup vs baseline: 1.0367x; 1.0003x over previous
.LBB0_971:
	s_waitcnt vmcnt(0)
	v_mov_b32_e32 v2, v213
	s_and_b64 vcc, exec, s[40:41]
	s_cbranch_vccnz .LBB0_982
	v_lshlrev_b32_e32 v1, 2, v2
	v_and_b32_e32 v4, 0x7c, v1
	v_readlane_b32 s4, v254, 13
	v_lshlrev_b32_e32 v8, 2, v4
	v_lshlrev_b32_e32 v4, 1, v4
	v_mov_b32_e32 v5, v0
	v_readlane_b32 s5, v254, 14
	v_ashrrev_i32_e32 v6, 5, v2
	s_movk_i32 s3, 0x80
	v_lshl_add_u64 v[4:5], s[4:5], 0, v[4:5]
	v_readlane_b32 s4, v255, 19
	v_cmp_gt_i32_e32 vcc, s3, v2
	s_lshl_b32 s3, s4, 7
	v_lshlrev_b32_e32 v12, 7, v6
	v_add_u32_e32 v10, s3, v2
	v_add_u32_e32 v14, 0x800, v12
	v_add_u32_e32 v16, 0x1000, v12
	v_add_u32_e32 v18, 0x1800, v12
	v_add_u32_e32 v20, 0x2000, v12
	v_add_u32_e32 v22, 0x2800, v12
	v_add_u32_e32 v24, 0x3000, v12
	v_add_u32_e32 v26, 0x3800, v12
	v_readlane_b32 s6, v254, 21
	v_readlane_b32 s40, v252, 10
	v_add_u32_e32 v28, 0, v8
	v_readlane_b32 s5, v255, 20
	v_lshlrev_b32_e32 v29, 9, v6
	v_and_b32_e32 v7, 63, v2
	v_ashrrev_i32_e32 v30, 4, v2
	v_ashrrev_i32_e32 v11, 31, v10
	v_ashrrev_i32_e32 v13, 31, v12
	v_ashrrev_i32_e32 v15, 31, v14
	v_ashrrev_i32_e32 v17, 31, v16
	v_ashrrev_i32_e32 v19, 31, v18
	v_ashrrev_i32_e32 v21, 31, v20
	v_ashrrev_i32_e32 v23, 31, v22
	v_ashrrev_i32_e32 v25, 31, v24
	v_ashrrev_i32_e32 v27, 31, v26
	v_mov_b32_e32 v9, v0
	v_readlane_b32 s7, v254, 22
	v_readlane_b32 s42, v252, 12
	v_readlane_b32 s43, v252, 13
	v_readlane_b32 s16, v253, 57
	v_readlane_b32 s18, v254, 19
	v_ashrrev_i32_e32 v3, 31, v2
	v_add_u32_e32 v1, 0, v1
	v_cmp_eq_u32_e64 s[4:5], 0, v7
	v_lshl_add_u32 v34, v6, 2, 0
	v_lshl_add_u64 v[6:7], s[72:73], 0, v[8:9]
	v_lshl_add_u64 v[8:9], s[6:7], 0, v[8:9]
	v_lshl_add_u64 v[10:11], v[10:11], 2, s[42:43]
	v_lshlrev_b64 v[12:13], 2, v[12:13]
	v_lshlrev_b64 v[14:15], 2, v[14:15]
	v_lshlrev_b64 v[16:17], 2, v[16:17]
	v_lshlrev_b64 v[18:19], 2, v[18:19]
	v_lshlrev_b64 v[20:21], 2, v[20:21]
	v_lshlrev_b64 v[22:23], 2, v[22:23]
	v_lshlrev_b64 v[24:25], 2, v[24:25]
	v_lshlrev_b64 v[26:27], 2, v[26:27]
	v_add_u32_e32 v35, v28, v29
	v_add_u32_e32 v36, 0, v30
	s_mov_b32 s12, s2
	v_readlane_b32 s17, v253, 58
	v_readlane_b32 s19, v254, 20
	v_readlane_b32 s41, v252, 11
	v_readlane_b32 s44, v252, 14
	v_readlane_b32 s45, v252, 15
	v_readlane_b32 s46, v252, 16
	v_readlane_b32 s47, v252, 17
	v_readlane_b32 s48, v252, 18
	v_readlane_b32 s49, v252, 19
	v_readlane_b32 s50, v252, 20
	v_readlane_b32 s51, v252, 21
	v_readlane_b32 s52, v252, 22
	v_readlane_b32 s53, v252, 23
	v_readlane_b32 s54, v252, 24
	v_readlane_b32 s55, v252, 25
	s_ashr_i32 s100, s12, 3
	s_add_i32 s100, s100, s3
	s_ashr_i32 s101, s100, 31
	s_lshl_b64 s[100:101], s[100:101], 19
	s_and_b32 s98, s12, 7
	s_lshl_b32 s98, s98, 16
	s_or_b32 s100, s100, s98
	v_lshl_add_u64 v[80:81], v[6:7], 0, s[100:101]
	v_lshl_add_u64 v[42:43], v[80:81], 0, v[12:13]
	global_load_dwordx4 v[100:103], v[42:43], off
	v_lshl_add_u64 v[44:45], v[80:81], 0, v[14:15]
	global_load_dwordx4 v[104:107], v[44:45], off
	v_lshl_add_u64 v[46:47], v[80:81], 0, v[16:17]
	global_load_dwordx4 v[108:111], v[46:47], off
	v_lshl_add_u64 v[48:49], v[80:81], 0, v[18:19]
	global_load_dwordx4 v[112:115], v[48:49], off
	v_lshl_add_u64 v[50:51], v[80:81], 0, v[20:21]
	global_load_dwordx4 v[116:119], v[50:51], off
	v_lshl_add_u64 v[52:53], v[80:81], 0, v[22:23]
	global_load_dwordx4 v[120:123], v[52:53], off
	v_lshl_add_u64 v[54:55], v[80:81], 0, v[24:25]
	global_load_dwordx4 v[124:127], v[54:55], off
	v_lshl_add_u64 v[56:57], v[80:81], 0, v[26:27]
	global_load_dwordx4 v[128:131], v[56:57], off
	s_branch .LBB0_974

.Lhs_ld1:
	s_or_b64 exec, exec, s[10:11]
	s_add_i32 s6, s6, s3
	s_ashr_i32 s7, s6, 31
	v_lshl_add_u64 v[90:91], s[8:9], 1, v[4:5]
	s_lshl_b64 s[6:7], s[6:7], 19
	s_lshl_b32 s8, s13, 16
	s_or_b32 s6, s6, s8
	v_lshl_add_u64 v[32:33], v[6:7], 0, s[6:7]
	v_lshl_add_u64 v[30:31], v[8:9], 0, s[6:7]
	global_load_dwordx2 v[90:91], v[90:91], off
	s_and_saveexec_b64 s[10:11], vcc
	s_cbranch_execz .Lhs_w1
	s_waitcnt vmcnt(1)
	v_lshlrev_b32_e32 v70, 16, v70
	v_lshlrev_b32_e32 v71, 16, v71
	ds_write2st64_b32 v1, v70, v71 offset1:2
.Lhs_w1:
	s_or_b64 exec, exec, s[10:11]
	s_waitcnt lgkmcnt(0)
	s_barrier
	ds_read_b32 v132, v34 offset:512
	ds_read_b32 v134, v34
	ds_read_b32 v136, v34 offset:576
	ds_read_b32 v138, v34 offset:64
	ds_read_b32 v140, v34 offset:640
	ds_read_b32 v142, v34 offset:128
	ds_read_b32 v144, v34 offset:704
	ds_read_b32 v146, v34 offset:192
	s_waitcnt lgkmcnt(7)
	ds_read_b32 v148, v34 offset:768
	ds_read_b32 v150, v34 offset:256
	ds_read_b32 v152, v34 offset:832
	ds_read_b32 v154, v34 offset:320
	ds_read_b32 v156, v34 offset:896
	ds_read_b32 v158, v34 offset:384
	ds_read_b32 v160, v34 offset:960
	ds_read_b32 v162, v34 offset:448
	s_waitcnt vmcnt(0)
	v_lshlrev_b32_e32 v37, 16, v90
	v_and_b32_e32 v39, 0xffff0000, v90
	v_lshlrev_b32_e32 v38, 16, v91
	v_and_b32_e32 v40, 0xffff0000, v91
	s_waitcnt lgkmcnt(0)
	v_sub_f32_e32 v73, v39, v101
	v_sub_f32_e32 v72, v37, v100
	v_sub_f32_e32 v75, v40, v103
	v_sub_f32_e32 v74, v38, v102
	v_pk_fma_f32 v[102:103], v[74:75], v[132:133], v[102:103] op_sel_hi:[1,0,1]
	v_pk_fma_f32 v[100:101], v[72:73], v[132:133], v[100:101] op_sel_hi:[1,0,1]
	v_lshl_add_u64 v[42:43], v[30:31], 0, v[12:13]
	global_store_dwordx4 v[42:43], v[100:103], off
	v_pk_fma_f32 v[76:77], v[100:101], v[134:135], 0 op_sel_hi:[1,0,0]
	v_pk_fma_f32 v[78:79], v[102:103], v[134:135], 0 op_sel_hi:[1,0,0]
	v_sub_f32_e32 v73, v39, v105
	v_sub_f32_e32 v72, v37, v104
	v_sub_f32_e32 v75, v40, v107
	v_sub_f32_e32 v74, v38, v106
	v_pk_fma_f32 v[106:107], v[74:75], v[136:137], v[106:107] op_sel_hi:[1,0,1]
	v_pk_fma_f32 v[104:105], v[72:73], v[136:137], v[104:105] op_sel_hi:[1,0,1]
	v_lshl_add_u64 v[44:45], v[30:31], 0, v[14:15]
	global_store_dwordx4 v[44:45], v[104:107], off
	v_pk_fma_f32 v[78:79], v[106:107], v[138:139], v[78:79] op_sel_hi:[1,0,1]
	v_pk_fma_f32 v[76:77], v[104:105], v[138:139], v[76:77] op_sel_hi:[1,0,1]
	v_sub_f32_e32 v73, v39, v109
	v_sub_f32_e32 v72, v37, v108
	v_sub_f32_e32 v75, v40, v111
	v_sub_f32_e32 v74, v38, v110
	v_pk_fma_f32 v[110:111], v[74:75], v[140:141], v[110:111] op_sel_hi:[1,0,1]
	v_pk_fma_f32 v[108:109], v[72:73], v[140:141], v[108:109] op_sel_hi:[1,0,1]
	v_lshl_add_u64 v[46:47], v[30:31], 0, v[16:17]
	global_store_dwordx4 v[46:47], v[108:111], off
	v_pk_fma_f32 v[78:79], v[110:111], v[142:143], v[78:79] op_sel_hi:[1,0,1]
	v_pk_fma_f32 v[76:77], v[108:109], v[142:143], v[76:77] op_sel_hi:[1,0,1]
	v_sub_f32_e32 v73, v39, v113
	v_sub_f32_e32 v72, v37, v112
	v_sub_f32_e32 v75, v40, v115
	v_sub_f32_e32 v74, v38, v114
	v_pk_fma_f32 v[114:115], v[74:75], v[144:145], v[114:115] op_sel_hi:[1,0,1]
	v_pk_fma_f32 v[112:113], v[72:73], v[144:145], v[112:113] op_sel_hi:[1,0,1]
	v_lshl_add_u64 v[48:49], v[30:31], 0, v[18:19]
	global_store_dwordx4 v[48:49], v[112:115], off
	v_pk_fma_f32 v[78:79], v[114:115], v[146:147], v[78:79] op_sel_hi:[1,0,1]
	v_pk_fma_f32 v[76:77], v[112:113], v[146:147], v[76:77] op_sel_hi:[1,0,1]
	v_sub_f32_e32 v73, v39, v117
	v_sub_f32_e32 v72, v37, v116
	v_sub_f32_e32 v75, v40, v119
	v_sub_f32_e32 v74, v38, v118
	v_pk_fma_f32 v[118:119], v[74:75], v[148:149], v[118:119] op_sel_hi:[1,0,1]
	v_pk_fma_f32 v[116:117], v[72:73], v[148:149], v[116:117] op_sel_hi:[1,0,1]
	v_lshl_add_u64 v[50:51], v[30:31], 0, v[20:21]
	global_store_dwordx4 v[50:51], v[116:119], off
	v_pk_fma_f32 v[78:79], v[118:119], v[150:151], v[78:79] op_sel_hi:[1,0,1]
	v_pk_fma_f32 v[76:77], v[116:117], v[150:151], v[76:77] op_sel_hi:[1,0,1]
	v_sub_f32_e32 v73, v39, v121
	v_sub_f32_e32 v72, v37, v120
	v_sub_f32_e32 v75, v40, v123
	v_sub_f32_e32 v74, v38, v122
	v_pk_fma_f32 v[122:123], v[74:75], v[152:153], v[122:123] op_sel_hi:[1,0,1]
	v_pk_fma_f32 v[120:121], v[72:73], v[152:153], v[120:121] op_sel_hi:[1,0,1]
	v_lshl_add_u64 v[52:53], v[30:31], 0, v[22:23]
	global_store_dwordx4 v[52:53], v[120:123], off
	v_pk_fma_f32 v[78:79], v[122:123], v[154:155], v[78:79] op_sel_hi:[1,0,1]
	v_pk_fma_f32 v[76:77], v[120:121], v[154:155], v[76:77] op_sel_hi:[1,0,1]
	v_sub_f32_e32 v73, v39, v125
	v_sub_f32_e32 v72, v37, v124
	v_sub_f32_e32 v75, v40, v127
	v_sub_f32_e32 v74, v38, v126
	v_pk_fma_f32 v[126:127], v[74:75], v[156:157], v[126:127] op_sel_hi:[1,0,1]
	v_pk_fma_f32 v[124:125], v[72:73], v[156:157], v[124:125] op_sel_hi:[1,0,1]
	v_lshl_add_u64 v[54:55], v[30:31], 0, v[24:25]
	global_store_dwordx4 v[54:55], v[124:127], off
	v_pk_fma_f32 v[78:79], v[126:127], v[158:159], v[78:79] op_sel_hi:[1,0,1]
	v_pk_fma_f32 v[76:77], v[124:125], v[158:159], v[76:77] op_sel_hi:[1,0,1]
	v_sub_f32_e32 v73, v39, v129
	v_sub_f32_e32 v72, v37, v128
	v_sub_f32_e32 v75, v40, v131
	v_sub_f32_e32 v74, v38, v130
	v_pk_fma_f32 v[130:131], v[74:75], v[160:161], v[130:131] op_sel_hi:[1,0,1]
	v_pk_fma_f32 v[128:129], v[72:73], v[160:161], v[128:129] op_sel_hi:[1,0,1]
	v_lshl_add_u64 v[56:57], v[30:31], 0, v[26:27]
	global_store_dwordx4 v[56:57], v[128:131], off
	v_pk_fma_f32 v[78:79], v[130:131], v[162:163], v[78:79] op_sel_hi:[1,0,1]
	v_pk_fma_f32 v[76:77], v[128:129], v[162:163], v[76:77] op_sel_hi:[1,0,1]
	ds_write_b128 v35, v[76:79] offset:1024
	v_mov_b32_e32 v30, 0
	s_add_i32 s99, s12, s26
	s_cmpk_lt_i32 s99, 0x400
	s_cbranch_scc0 .Lhs_nopf
	s_ashr_i32 s100, s99, 3
	s_add_i32 s100, s100, s3
	s_ashr_i32 s101, s100, 31
	s_lshl_b64 s[100:101], s[100:101], 19
	s_and_b32 s98, s99, 7
	s_lshl_b32 s98, s98, 16
	s_or_b32 s100, s100, s98
	v_lshl_add_u64 v[80:81], v[6:7], 0, s[100:101]
	v_lshl_add_u64 v[42:43], v[80:81], 0, v[12:13]
	global_load_dwordx4 v[100:103], v[42:43], off
	v_lshl_add_u64 v[44:45], v[80:81], 0, v[14:15]
	global_load_dwordx4 v[104:107], v[44:45], off
	v_lshl_add_u64 v[46:47], v[80:81], 0, v[16:17]
	global_load_dwordx4 v[108:111], v[46:47], off
	v_lshl_add_u64 v[48:49], v[80:81], 0, v[18:19]
	global_load_dwordx4 v[112:115], v[48:49], off
	v_lshl_add_u64 v[50:51], v[80:81], 0, v[20:21]
	global_load_dwordx4 v[116:119], v[50:51], off
	v_lshl_add_u64 v[52:53], v[80:81], 0, v[22:23]
	global_load_dwordx4 v[120:123], v[52:53], off
	v_lshl_add_u64 v[54:55], v[80:81], 0, v[24:25]
	global_load_dwordx4 v[124:127], v[54:55], off
	v_lshl_add_u64 v[56:57], v[80:81], 0, v[26:27]
	global_load_dwordx4 v[128:131], v[56:57], off
.Lhs_nopf:
	s_waitcnt lgkmcnt(0)
	s_barrier
	s_and_saveexec_b64 s[8:9], vcc
	s_cbranch_execz .LBB0_980
	ds_read2st64_b32 v[132:133], v1 offset0:4 offset1:6
	ds_read2st64_b32 v[134:135], v1 offset0:8 offset1:10
	ds_read2st64_b32 v[136:137], v1 offset0:12 offset1:14
	ds_read2st64_b32 v[138:139], v1 offset0:16 offset1:18
	ds_read2st64_b32 v[140:141], v1 offset0:20 offset1:22
	ds_read2st64_b32 v[142:143], v1 offset0:24 offset1:26
	ds_read2st64_b32 v[144:145], v1 offset0:28 offset1:30
	ds_read2st64_b32 v[146:147], v1 offset0:32 offset1:34
	v_xor_b32_e32 v33, 1, v216
	s_waitcnt lgkmcnt(0)
	v_add_f32_e32 v30, 0, v132
	v_add_f32_e32 v32, v30, v133
	v_add_f32_e32 v30, v32, v134
	v_add_f32_e32 v32, v30, v135
	v_add_f32_e32 v30, v32, v136
	v_add_f32_e32 v32, v30, v137
	v_add_f32_e32 v30, v32, v138
	v_add_f32_e32 v32, v30, v139
	v_add_f32_e32 v30, v32, v140
	v_add_f32_e32 v32, v30, v141
	v_add_f32_e32 v30, v32, v142
	v_add_f32_e32 v32, v30, v143
	v_add_f32_e32 v30, v32, v144
	v_add_f32_e32 v32, v30, v145
	v_add_f32_e32 v30, v32, v146
	v_and_b32_e32 v32, 64, v216
	v_add_u32_e32 v32, 64, v32
	v_cmp_lt_i32_e64 s[6:7], v33, v32
	v_add_f32_e32 v30, v30, v147
	v_mul_f32_e32 v31, v30, v30
	v_cndmask_b32_e64 v33, v216, v33, s[6:7]
	v_lshlrev_b32_e32 v33, 2, v33
	ds_bpermute_b32 v31, v33, v31
	v_xor_b32_e32 v33, 2, v216
	v_cmp_lt_i32_e64 s[6:7], v33, v32
	s_waitcnt lgkmcnt(0)
	v_fmac_f32_e32 v31, v30, v30
	v_cndmask_b32_e64 v33, v216, v33, s[6:7]
	v_lshlrev_b32_e32 v33, 2, v33
	ds_bpermute_b32 v33, v33, v31
	s_waitcnt lgkmcnt(0)
	v_add_f32_e32 v31, v31, v33
	v_xor_b32_e32 v33, 4, v216
	v_cmp_lt_i32_e64 s[6:7], v33, v32
	s_nop 1
	v_cndmask_b32_e64 v33, v216, v33, s[6:7]
	v_lshlrev_b32_e32 v33, 2, v33
	ds_bpermute_b32 v33, v33, v31
	s_waitcnt lgkmcnt(0)
	v_add_f32_e32 v31, v31, v33
	v_xor_b32_e32 v33, 8, v216
	v_cmp_lt_i32_e64 s[6:7], v33, v32
	s_nop 1
	v_cndmask_b32_e64 v33, v216, v33, s[6:7]
	v_lshlrev_b32_e32 v33, 2, v33
	ds_bpermute_b32 v33, v33, v31
	s_waitcnt lgkmcnt(0)
	v_add_f32_e32 v31, v31, v33
	v_xor_b32_e32 v33, 16, v216
	v_cmp_lt_i32_e64 s[6:7], v33, v32
	s_nop 1
	v_cndmask_b32_e64 v33, v216, v33, s[6:7]
	v_lshlrev_b32_e32 v33, 2, v33
	ds_bpermute_b32 v33, v33, v31
	s_waitcnt lgkmcnt(0)
	v_add_f32_e32 v31, v31, v33
	v_xor_b32_e32 v33, 32, v216
	v_cmp_lt_i32_e64 s[6:7], v33, v32
	s_nop 1
	v_cndmask_b32_e64 v32, v216, v33, s[6:7]
	v_lshlrev_b32_e32 v32, 2, v32
	ds_bpermute_b32 v32, v32, v31
	s_and_saveexec_b64 s[6:7], s[4:5]
	s_cbranch_execz .LBB0_979
	s_waitcnt lgkmcnt(0)
	v_add_f32_e32 v31, v31, v32
	ds_write_b32 v36, v31 offset:9216
